# v035 + diff-attention unit to workgroup remap: the four workgroups sharing a (batch, head) K/V stream on one XCD, to cut K/V fabric traffic (energy)
# speedup vs baseline: 1.0051x; 1.0051x over previous
; __device__ __forceinline__ void attention_phase(const Params& p, LAS unsigned char* lds, int G, int blk) {
;     float s1 = 0.f, s2 = 0.f;
;     for (int i = 0; i < 64; ++i) { s1 += p.lq1[i] * p.lk1[i]; s2 += p.lq2[i] * p.lk2[i]; }
;     const float lam = expf(s1) - expf(s2) + 0.2f;
;     const int v = (G % 8 == 0) ? (blk % 8) * (G / 8) + blk / 8 : blk;
;     for (int rep = 0; rep < PROBE_DIFF_REPS; ++rep)
;     for (int u = v; u < 1024; u += G) {
;         const int bh = (u & 255) >> 2, s = u & 3, i = u >> 8;
;         const int qb = (i == 0) ? s : (i == 1) ? 7 - s : (i == 2) ? 8 + s : 15 - s;
.LBB0_265:
	v_mul_f32_e32 v2, 0x3fb8aa3b, v0
	s_mov_b32 s0, 0x3fb8aa3b
	v_rndne_f32_e32 v3, v2
	v_sub_f32_e32 v4, v2, v3
	v_fma_f32 v2, v0, s0, -v2
	v_fmac_f32_e32 v2, 0x32a5705f, v0
	v_add_f32_e32 v2, v4, v2
	v_exp_f32_e32 v2, v2
	v_cvt_i32_f32_e32 v3, v3
	s_add_u32 s18, s28, 0x16000000
	s_addc_u32 s19, s29, 0
	s_add_u32 s14, s28, 0x26000000
	v_ldexp_f32 v2, v2, v3
	v_mul_f32_e32 v3, 0x3fb8aa3b, v1
	v_rndne_f32_e32 v4, v3
	s_addc_u32 s15, s29, 0
	v_sub_f32_e32 v5, v3, v4
	v_fma_f32 v3, v1, s0, -v3
	s_add_u32 s17, s28, 0x3e000000
	v_fmac_f32_e32 v3, 0x32a5705f, v1
	s_addc_u32 s26, s29, 0
	v_add_f32_e32 v3, v5, v3
	s_add_u32 s27, s28, 0x36000000
	v_exp_f32_e32 v3, v3
	v_cvt_i32_f32_e32 v4, v4
	s_addc_u32 s35, s29, 0
	s_mov_b32 s1, 0xc2ce8ed0
	s_add_u32 s68, s28, 0x2e000000
	v_cmp_ngt_f32_e32 vcc, s1, v0
	s_mov_b32 s3, 0x42b17218
	s_addc_u32 s69, s29, 0
	v_cndmask_b32_e32 v2, 0, v2, vcc
	v_mov_b32_e32 v5, 0x7f800000
	v_cmp_nlt_f32_e32 vcc, s3, v0
	s_add_u32 s20, s28, 0x26008000
	s_addc_u32 s21, s29, 0
	v_cndmask_b32_e32 v0, v5, v2, vcc
	v_ldexp_f32 v2, v3, v4
	v_cmp_ngt_f32_e32 vcc, s1, v1
	s_add_u32 s38, s28, 0x36004000
	s_addc_u32 s39, s29, 0
	v_cndmask_b32_e32 v2, 0, v2, vcc
	v_cmp_nlt_f32_e32 vcc, s3, v1
	s_add_u32 s40, s28, 0x36404000
	v_mbcnt_hi_u32_b32 v191, -1, v190
	v_cndmask_b32_e32 v1, v5, v2, vcc
	v_sub_f32_e32 v0, v0, v1
	s_mov_b32 s7, 0
	v_add_f32_e32 v161, 0x3e4ccccd, v0
	s_addc_u32 s41, s29, 0
	v_mov_b32_e32 v1, 0
	s_mov_b64 s[42:43], 0x2000
	s_mov_b32 s8, 0x3f803f80
	s_mov_b32 s70, 0x41000000
	s_mov_b64 s[46:47], 0x1a00
	s_mov_b64 s[48:49], 0x1b00
	s_mov_b64 s[50:51], 0x1c00
	s_mov_b64 s[52:53], 0x1d00
	s_mov_b64 s[58:59], 0x1e00
	s_mov_b64 s[62:63], 0x1f00
	v_mov_b32_e32 v192, 0x358637bd
	s_mov_b32 s71, 0xf800000
	v_mov_b32_e32 v193, 0x260
	v_and_b32_e32 v194, 64, v191
	s_mov_b32 s72, s16
	s_cmpk_lg_u32 s30, 0x100
	s_cbranch_scc1 .Lxcd_ident
	s_and_b32 s0, s16, 7
	s_lshl_b32 s0, s0, 2
	s_bfe_u32 s1, s16, 0x20003
	s_or_b32 s0, s0, s1
	s_and_b32 s1, s16, 0xe0
	s_or_b32 s72, s0, s1
.Lxcd_ident:
	s_branch .LBB0_268
